# v8 plus hand-written scan: DEC staged once in LDS by LDS-DMA, sliding window of 32 U loads with counted vmcnt
# baseline (speedup 1.0000x reference)
; __device__ __forceinline__ void scan_phase(bf16* U, bf16* So, const float* DEC, int bid, int G, int tid) {
;     if (tid >= 256) return;
;     for (int e = bid * 256 + tid; e < NH * HV * (HK / 2); e += G * 256) {
;         const int hd = e >> 14, rem = e & 16383, v = rem >> 6, kp = rem & 63;
;         unsigned* up = (unsigned*)(U + ((size_t)hd * HV + v) * HK + 2 * kp);
;         unsigned* op = (unsigned*)(So + ((size_t)hd * HV + v) * HK + 2 * kp);
;         const f32x2* dp = (const f32x2*)(DEC + hd * HK + 2 * kp);
;         float s0 = 0.f, s1 = 0.f;
;         for (int c0 = 0; c0 < NCH; c0 += SCAN_B) {
;             unsigned ub[SCAN_B]; f32x2 db[SCAN_B];
; #pragma unroll
;             for (int i = 0; i < SCAN_B; ++i) { ub[i] = up[(size_t)(c0 + i) * (NH * HV * HK / 2)]; db[i] = dp[(size_t)(c0 + i) * (DQK / 2)]; }
; __global__ void __launch_bounds__(NTHR, 2) fwd_megakernel(Args a) {
;     ...
;                 { PHASE_IDS if (tid < 256) scan_phase(Ub, Ub, DEC, bid, G, tid); else conv_phase(PROJ, a.in[7] + (size_t)l * 3 * DCONV, Yb, bid * 256 + (tid - 256), G * 256); }
.LBB0_480:
	s_or_b64 exec, exec, s[2:3]
	s_waitcnt vmcnt(22) lgkmcnt(0)
	v_mov_b32_e32 v4, v168
	s_movk_i32 s2, 0xff
	s_barrier
	v_readfirstlane_b32 s27, v168
	s_lshr_b32 s32, s18, 6
	s_lshl_b32 s32, s32, 9
	s_lshr_b32 s27, s27, 6
	s_lshl_b32 s38, s27, 16
	s_add_u32 s32, s32, s38
	s_add_u32 s38, s80, 0x24e00000
	s_addc_u32 s39, s81, 0
	s_add_u32 s38, s38, s32
	s_addc_u32 s39, s39, 0
	v_and_b32_e32 v6, 63, v168
	v_lshrrev_b32_e32 v7, 5, v6
	v_and_b32_e32 v6, 31, v6
	v_lshlrev_b32_e32 v6, 4, v6
	v_lshl_add_u32 v6, v7, 11, v6
	s_lshl_b32 s27, s27, 14
	s_add_i32 m0, s27, 0x0
	s_nop 0
	global_load_lds_dwordx4 v6, s[38:39]
	s_add_u32 s38, s38, 0x1000
	s_addc_u32 s39, s39, 0
	s_add_i32 m0, s27, 0x400
	s_nop 0
	global_load_lds_dwordx4 v6, s[38:39]
	s_add_u32 s38, s38, 0x1000
	s_addc_u32 s39, s39, 0
	s_add_i32 m0, s27, 0x800
	s_nop 0
	global_load_lds_dwordx4 v6, s[38:39]
	s_add_u32 s38, s38, 0x1000
	s_addc_u32 s39, s39, 0
	s_add_i32 m0, s27, 0xc00
	s_nop 0
	global_load_lds_dwordx4 v6, s[38:39]
	s_add_u32 s38, s38, 0x1000
	s_addc_u32 s39, s39, 0
	s_add_i32 m0, s27, 0x1000
	s_nop 0
	global_load_lds_dwordx4 v6, s[38:39]
	s_add_u32 s38, s38, 0x1000
	s_addc_u32 s39, s39, 0
	s_add_i32 m0, s27, 0x1400
	s_nop 0
	global_load_lds_dwordx4 v6, s[38:39]
	s_add_u32 s38, s38, 0x1000
	s_addc_u32 s39, s39, 0
	s_add_i32 m0, s27, 0x1800
	s_nop 0
	global_load_lds_dwordx4 v6, s[38:39]
	s_add_u32 s38, s38, 0x1000
	s_addc_u32 s39, s39, 0
	s_add_i32 m0, s27, 0x1c00
	s_nop 0
	global_load_lds_dwordx4 v6, s[38:39]
	s_add_u32 s38, s38, 0x1000
	s_addc_u32 s39, s39, 0
	s_add_i32 m0, s27, 0x2000
	s_nop 0
	global_load_lds_dwordx4 v6, s[38:39]
	s_add_u32 s38, s38, 0x1000
	s_addc_u32 s39, s39, 0
	s_add_i32 m0, s27, 0x2400
	s_nop 0
	global_load_lds_dwordx4 v6, s[38:39]
	s_add_u32 s38, s38, 0x1000
	s_addc_u32 s39, s39, 0
	s_add_i32 m0, s27, 0x2800
	s_nop 0
	global_load_lds_dwordx4 v6, s[38:39]
	s_add_u32 s38, s38, 0x1000
	s_addc_u32 s39, s39, 0
	s_add_i32 m0, s27, 0x2c00
	s_nop 0
	global_load_lds_dwordx4 v6, s[38:39]
	s_add_u32 s38, s38, 0x1000
	s_addc_u32 s39, s39, 0
	s_add_i32 m0, s27, 0x3000
	s_nop 0
	global_load_lds_dwordx4 v6, s[38:39]
	s_add_u32 s38, s38, 0x1000
	s_addc_u32 s39, s39, 0
	s_add_i32 m0, s27, 0x3400
	s_nop 0
	global_load_lds_dwordx4 v6, s[38:39]
	s_add_u32 s38, s38, 0x1000
	s_addc_u32 s39, s39, 0
	s_add_i32 m0, s27, 0x3800
	s_nop 0
	global_load_lds_dwordx4 v6, s[38:39]
	s_add_u32 s38, s38, 0x1000
	s_addc_u32 s39, s39, 0
	s_add_i32 m0, s27, 0x3c00
	s_nop 0
	global_load_lds_dwordx4 v6, s[38:39]
	s_waitcnt vmcnt(0)
	s_barrier
	s_nop 0
	v_cmp_lt_i32_e32 vcc, s2, v4
	s_and_saveexec_b64 s[2:3], vcc
	s_xor_b64 s[44:45], exec, s[2:3]
	s_cbranch_execz .LBB0_489
	v_readlane_b32 s2, v249, 62
	s_nop 1
	v_add_u32_e32 v74, s2, v4
	s_mov_b32 s2, 0x20000
	v_cmp_gt_i32_e32 vcc, s2, v74
	s_and_saveexec_b64 s[46:47], vcc
	s_cbranch_execz .LBB0_488
	v_lshlrev_b32_e32 v75, 3, v74
	s_mov_b64 s[48:49], 0

; __device__ __forceinline__ float bflo(unsigned u) { return __uint_as_float(u << 16); }
; __device__ __forceinline__ float bfhi(unsigned u) { return __uint_as_float(u & 0xffff0000u); }
; __device__ __forceinline__ unsigned pk2(float lo, float hi) { return pg8::cvt_pk_bf16(lo, hi); }
; __device__ __forceinline__ void scan_phase(bf16* U, bf16* So, const float* DEC, int bid, int G, int tid) {
;     ...
;     for (int e = bid * 256 + tid; e < NH * HV * (HK / 2); e += G * 256) {
;         const int hd = e >> 14, rem = e & 16383, v = rem >> 6, kp = rem & 63;
;         unsigned* up = (unsigned*)(U + ((size_t)hd * HV + v) * HK + 2 * kp);
;         unsigned* op = (unsigned*)(So + ((size_t)hd * HV + v) * HK + 2 * kp);
;         const f32x2* dp = (const f32x2*)(DEC + hd * HK + 2 * kp);
;         float s0 = 0.f, s1 = 0.f;
;         for (int c0 = 0; c0 < NCH; c0 += SCAN_B) {
;             unsigned ub[SCAN_B]; f32x2 db[SCAN_B];
; #pragma unroll
;             for (int i = 0; i < SCAN_B; ++i) { ub[i] = up[(size_t)(c0 + i) * (NH * HV * HK / 2)]; db[i] = dp[(size_t)(c0 + i) * (DQK / 2)]; }
; #pragma unroll
;             for (int i = 0; i < SCAN_B; ++i) { op[(size_t)(c0 + i) * (NH * HV * HK / 2)] = pk2(s0, s1); s0 = db[i].x * s0 + bflo(ub[i]); s1 = db[i].y * s1 + bfhi(ub[i]); }
.LBB0_489:
	s_andn2_saveexec_b64 s[2:3], s[44:45]
	s_cbranch_execz .LBB0_496
	v_readlane_b32 s4, v249, 61
	s_nop 1
	v_add_u32_e32 v100, s4, v4
	s_mov_b32 s4, 0x10000
	v_cmp_gt_i32_e32 vcc, s4, v100
	s_and_saveexec_b64 s[4:5], vcc
	s_cbranch_execz .LBB0_495
	v_readfirstlane_b32 s27, v168
	s_lshl_b32 s32, s18, 2
	s_lshr_b32 s27, s27, 6
	s_add_u32 s27, s27, s32
	s_lshl_b32 s27, s27, 8
	v_and_b32_e32 v11, 63, v168
	v_lshl_add_u32 v10, v11, 2, s27
	v_lshlrev_b32_e32 v11, 3, v11
	s_add_u32 s52, s80, 0x1ee00000
	s_addc_u32 s53, s81, 0
	s_mov_b64 s[54:55], s[52:53]
	v_mov_b32_e32 v8, 0
	v_mov_b32_e32 v9, 0
	global_load_dword v20, v10, s[52:53]
	s_add_u32 s52, s52, 0x40000
	s_addc_u32 s53, s53, 0
	global_load_dword v21, v10, s[52:53]
	s_add_u32 s52, s52, 0x40000
	s_addc_u32 s53, s53, 0
	global_load_dword v22, v10, s[52:53]
	s_add_u32 s52, s52, 0x40000
	s_addc_u32 s53, s53, 0
	global_load_dword v23, v10, s[52:53]
	s_add_u32 s52, s52, 0x40000
	s_addc_u32 s53, s53, 0
	global_load_dword v24, v10, s[52:53]
	s_add_u32 s52, s52, 0x40000
	s_addc_u32 s53, s53, 0
	global_load_dword v25, v10, s[52:53]
	s_add_u32 s52, s52, 0x40000
	s_addc_u32 s53, s53, 0
	global_load_dword v26, v10, s[52:53]
	s_add_u32 s52, s52, 0x40000
	s_addc_u32 s53, s53, 0
	global_load_dword v27, v10, s[52:53]
	s_add_u32 s52, s52, 0x40000
	s_addc_u32 s53, s53, 0
	global_load_dword v28, v10, s[52:53]
	s_add_u32 s52, s52, 0x40000
	s_addc_u32 s53, s53, 0
	global_load_dword v29, v10, s[52:53]
	s_add_u32 s52, s52, 0x40000
	s_addc_u32 s53, s53, 0
	global_load_dword v30, v10, s[52:53]
	s_add_u32 s52, s52, 0x40000
	s_addc_u32 s53, s53, 0
	global_load_dword v31, v10, s[52:53]
	s_add_u32 s52, s52, 0x40000
	s_addc_u32 s53, s53, 0
	global_load_dword v32, v10, s[52:53]
	s_add_u32 s52, s52, 0x40000
	s_addc_u32 s53, s53, 0
	global_load_dword v33, v10, s[52:53]
	s_add_u32 s52, s52, 0x40000
	s_addc_u32 s53, s53, 0
	global_load_dword v34, v10, s[52:53]
	s_add_u32 s52, s52, 0x40000
	s_addc_u32 s53, s53, 0
	global_load_dword v35, v10, s[52:53]
	s_add_u32 s52, s52, 0x40000
	s_addc_u32 s53, s53, 0
	global_load_dword v36, v10, s[52:53]
	s_add_u32 s52, s52, 0x40000
	s_addc_u32 s53, s53, 0
	global_load_dword v37, v10, s[52:53]
	s_add_u32 s52, s52, 0x40000
	s_addc_u32 s53, s53, 0
	global_load_dword v38, v10, s[52:53]
	s_add_u32 s52, s52, 0x40000
	s_addc_u32 s53, s53, 0
	global_load_dword v39, v10, s[52:53]
	s_add_u32 s52, s52, 0x40000
	s_addc_u32 s53, s53, 0
	global_load_dword v40, v10, s[52:53]
	s_add_u32 s52, s52, 0x40000
	s_addc_u32 s53, s53, 0
	global_load_dword v41, v10, s[52:53]
	s_add_u32 s52, s52, 0x40000
	s_addc_u32 s53, s53, 0
	global_load_dword v42, v10, s[52:53]
	s_add_u32 s52, s52, 0x40000
	s_addc_u32 s53, s53, 0
	global_load_dword v43, v10, s[52:53]
	s_add_u32 s52, s52, 0x40000
	s_addc_u32 s53, s53, 0
	global_load_dword v44, v10, s[52:53]
	s_add_u32 s52, s52, 0x40000
	s_addc_u32 s53, s53, 0
	global_load_dword v45, v10, s[52:53]
	s_add_u32 s52, s52, 0x40000
	s_addc_u32 s53, s53, 0
	global_load_dword v46, v10, s[52:53]
	s_add_u32 s52, s52, 0x40000
	s_addc_u32 s53, s53, 0
	global_load_dword v47, v10, s[52:53]
	s_add_u32 s52, s52, 0x40000
	s_addc_u32 s53, s53, 0
	global_load_dword v48, v10, s[52:53]
	s_add_u32 s52, s52, 0x40000
	s_addc_u32 s53, s53, 0
	global_load_dword v49, v10, s[52:53]
	s_add_u32 s52, s52, 0x40000
	s_addc_u32 s53, s53, 0
	global_load_dword v50, v10, s[52:53]
	s_add_u32 s52, s52, 0x40000
	s_addc_u32 s53, s53, 0
	global_load_dword v51, v10, s[52:53]
	s_add_u32 s52, s52, 0x40000
	s_addc_u32 s53, s53, 0
	ds_read_b64 v[52:53], v11 offset:0
	ds_read_b64 v[54:55], v11 offset:512
	ds_read_b64 v[56:57], v11 offset:1024
	ds_read_b64 v[58:59], v11 offset:1536
	ds_read_b64 v[60:61], v11 offset:2048
	ds_read_b64 v[62:63], v11 offset:2560
	ds_read_b64 v[64:65], v11 offset:3072
	ds_read_b64 v[66:67], v11 offset:3584
	s_waitcnt lgkmcnt(0)
	ds_read_b64 v[68:69], v11 offset:4096
	ds_read_b64 v[70:71], v11 offset:4608
	ds_read_b64 v[72:73], v11 offset:5120
	ds_read_b64 v[74:75], v11 offset:5632
	ds_read_b64 v[76:77], v11 offset:6144
	ds_read_b64 v[78:79], v11 offset:6656
	ds_read_b64 v[80:81], v11 offset:7168
	ds_read_b64 v[82:83], v11 offset:7680
	s_waitcnt vmcnt(31)
	v_cvt_pk_bf16_f32 v12, v8, v9
	global_store_dword v10, v12, s[54:55]
	s_add_u32 s54, s54, 0x40000
	s_addc_u32 s55, s55, 0
	v_lshlrev_b32_e32 v14, 16, v20
	v_and_b32_e32 v15, 0xffff0000, v20
	global_load_dword v20, v10, s[52:53]
	s_add_u32 s52, s52, 0x40000
	s_addc_u32 s53, s53, 0
	v_pk_fma_f32 v[8:9], v[8:9], v[52:53], v[14:15]
	s_waitcnt vmcnt(32)
	v_cvt_pk_bf16_f32 v13, v8, v9
	global_store_dword v10, v13, s[54:55]
	s_add_u32 s54, s54, 0x40000
	s_addc_u32 s55, s55, 0
	v_lshlrev_b32_e32 v14, 16, v21
	v_and_b32_e32 v15, 0xffff0000, v21
	global_load_dword v21, v10, s[52:53]
	s_add_u32 s52, s52, 0x40000
	s_addc_u32 s53, s53, 0
	v_pk_fma_f32 v[8:9], v[8:9], v[54:55], v[14:15]
	s_waitcnt vmcnt(33)
	v_cvt_pk_bf16_f32 v12, v8, v9
	global_store_dword v10, v12, s[54:55]
	s_add_u32 s54, s54, 0x40000
	s_addc_u32 s55, s55, 0
	v_lshlrev_b32_e32 v14, 16, v22
	v_and_b32_e32 v15, 0xffff0000, v22
	global_load_dword v22, v10, s[52:53]
	s_add_u32 s52, s52, 0x40000
	s_addc_u32 s53, s53, 0
	v_pk_fma_f32 v[8:9], v[8:9], v[56:57], v[14:15]
	s_waitcnt vmcnt(34)
	v_cvt_pk_bf16_f32 v13, v8, v9
	global_store_dword v10, v13, s[54:55]
	s_add_u32 s54, s54, 0x40000
	s_addc_u32 s55, s55, 0
	v_lshlrev_b32_e32 v14, 16, v23
	v_and_b32_e32 v15, 0xffff0000, v23
	global_load_dword v23, v10, s[52:53]
	s_add_u32 s52, s52, 0x40000
	s_addc_u32 s53, s53, 0
	v_pk_fma_f32 v[8:9], v[8:9], v[58:59], v[14:15]
	s_waitcnt vmcnt(35)
; __device__ __forceinline__ float bflo(unsigned u) { return __uint_as_float(u << 16); }
; __device__ __forceinline__ float bfhi(unsigned u) { return __uint_as_float(u & 0xffff0000u); }
; __device__ __forceinline__ unsigned pk2(float lo, float hi) { return pg8::cvt_pk_bf16(lo, hi); }
; __device__ __forceinline__ void scan_phase(bf16* U, bf16* So, const float* DEC, int bid, int G, int tid) {
;     ...
;         for (int c0 = 0; c0 < NCH; c0 += SCAN_B) {
;             unsigned ub[SCAN_B]; f32x2 db[SCAN_B];
; #pragma unroll
;             for (int i = 0; i < SCAN_B; ++i) { ub[i] = up[(size_t)(c0 + i) * (NH * HV * HK / 2)]; db[i] = dp[(size_t)(c0 + i) * (DQK / 2)]; }
; #pragma unroll
;             for (int i = 0; i < SCAN_B; ++i) { op[(size_t)(c0 + i) * (NH * HV * HK / 2)] = pk2(s0, s1); s0 = db[i].x * s0 + bflo(ub[i]); s1 = db[i].y * s1 + bfhi(ub[i]); }
	v_cvt_pk_bf16_f32 v12, v8, v9
	global_store_dword v10, v12, s[54:55]
	s_add_u32 s54, s54, 0x40000
	s_addc_u32 s55, s55, 0
	v_lshlrev_b32_e32 v14, 16, v24
	v_and_b32_e32 v15, 0xffff0000, v24
	global_load_dword v24, v10, s[52:53]
	s_add_u32 s52, s52, 0x40000
	s_addc_u32 s53, s53, 0
	v_pk_fma_f32 v[8:9], v[8:9], v[60:61], v[14:15]
	s_waitcnt vmcnt(36)
	v_cvt_pk_bf16_f32 v13, v8, v9
	global_store_dword v10, v13, s[54:55]
	s_add_u32 s54, s54, 0x40000
	s_addc_u32 s55, s55, 0
	v_lshlrev_b32_e32 v14, 16, v25
	v_and_b32_e32 v15, 0xffff0000, v25
	global_load_dword v25, v10, s[52:53]
	s_add_u32 s52, s52, 0x40000
	s_addc_u32 s53, s53, 0
	v_pk_fma_f32 v[8:9], v[8:9], v[62:63], v[14:15]
	s_waitcnt vmcnt(37)
	v_cvt_pk_bf16_f32 v12, v8, v9
	global_store_dword v10, v12, s[54:55]
	s_add_u32 s54, s54, 0x40000
	s_addc_u32 s55, s55, 0
	v_lshlrev_b32_e32 v14, 16, v26
	v_and_b32_e32 v15, 0xffff0000, v26
	global_load_dword v26, v10, s[52:53]
	s_add_u32 s52, s52, 0x40000
	s_addc_u32 s53, s53, 0
	v_pk_fma_f32 v[8:9], v[8:9], v[64:65], v[14:15]
	s_waitcnt vmcnt(38)
	v_cvt_pk_bf16_f32 v13, v8, v9
	global_store_dword v10, v13, s[54:55]
	s_add_u32 s54, s54, 0x40000
	s_addc_u32 s55, s55, 0
	v_lshlrev_b32_e32 v14, 16, v27
	v_and_b32_e32 v15, 0xffff0000, v27
	global_load_dword v27, v10, s[52:53]
	s_add_u32 s52, s52, 0x40000
	s_addc_u32 s53, s53, 0
	v_pk_fma_f32 v[8:9], v[8:9], v[66:67], v[14:15]
	s_waitcnt lgkmcnt(0)
	ds_read_b64 v[52:53], v11 offset:8192
	ds_read_b64 v[54:55], v11 offset:8704
	ds_read_b64 v[56:57], v11 offset:9216
	ds_read_b64 v[58:59], v11 offset:9728
	ds_read_b64 v[60:61], v11 offset:10240
	ds_read_b64 v[62:63], v11 offset:10752
	ds_read_b64 v[64:65], v11 offset:11264
	ds_read_b64 v[66:67], v11 offset:11776
	s_waitcnt vmcnt(39)
	v_cvt_pk_bf16_f32 v12, v8, v9
	global_store_dword v10, v12, s[54:55]
	s_add_u32 s54, s54, 0x40000
	s_addc_u32 s55, s55, 0
	v_lshlrev_b32_e32 v14, 16, v28
	v_and_b32_e32 v15, 0xffff0000, v28
	global_load_dword v28, v10, s[52:53]
	s_add_u32 s52, s52, 0x40000
	s_addc_u32 s53, s53, 0
	v_pk_fma_f32 v[8:9], v[8:9], v[68:69], v[14:15]
	s_waitcnt vmcnt(40)
	v_cvt_pk_bf16_f32 v13, v8, v9
	global_store_dword v10, v13, s[54:55]
	s_add_u32 s54, s54, 0x40000
	s_addc_u32 s55, s55, 0
	v_lshlrev_b32_e32 v14, 16, v29
	v_and_b32_e32 v15, 0xffff0000, v29
	global_load_dword v29, v10, s[52:53]
	s_add_u32 s52, s52, 0x40000
	s_addc_u32 s53, s53, 0
	v_pk_fma_f32 v[8:9], v[8:9], v[70:71], v[14:15]
	s_waitcnt vmcnt(41)
	v_cvt_pk_bf16_f32 v12, v8, v9
	global_store_dword v10, v12, s[54:55]
	s_add_u32 s54, s54, 0x40000
	s_addc_u32 s55, s55, 0
	v_lshlrev_b32_e32 v14, 16, v30
	v_and_b32_e32 v15, 0xffff0000, v30
	global_load_dword v30, v10, s[52:53]
	s_add_u32 s52, s52, 0x40000
	s_addc_u32 s53, s53, 0
	v_pk_fma_f32 v[8:9], v[8:9], v[72:73], v[14:15]
	s_waitcnt vmcnt(42)
	v_cvt_pk_bf16_f32 v13, v8, v9
	global_store_dword v10, v13, s[54:55]
	s_add_u32 s54, s54, 0x40000
	s_addc_u32 s55, s55, 0
	v_lshlrev_b32_e32 v14, 16, v31
	v_and_b32_e32 v15, 0xffff0000, v31
	global_load_dword v31, v10, s[52:53]
	s_add_u32 s52, s52, 0x40000
	s_addc_u32 s53, s53, 0
	v_pk_fma_f32 v[8:9], v[8:9], v[74:75], v[14:15]
	s_waitcnt vmcnt(43)
	v_cvt_pk_bf16_f32 v12, v8, v9
	global_store_dword v10, v12, s[54:55]
	s_add_u32 s54, s54, 0x40000
	s_addc_u32 s55, s55, 0
	v_lshlrev_b32_e32 v14, 16, v32
	v_and_b32_e32 v15, 0xffff0000, v32
	global_load_dword v32, v10, s[52:53]
	s_add_u32 s52, s52, 0x40000
	s_addc_u32 s53, s53, 0
	v_pk_fma_f32 v[8:9], v[8:9], v[76:77], v[14:15]
	s_waitcnt vmcnt(44)
	v_cvt_pk_bf16_f32 v13, v8, v9
	global_store_dword v10, v13, s[54:55]
	s_add_u32 s54, s54, 0x40000
	s_addc_u32 s55, s55, 0
	v_lshlrev_b32_e32 v14, 16, v33
	v_and_b32_e32 v15, 0xffff0000, v33
	global_load_dword v33, v10, s[52:53]
	s_add_u32 s52, s52, 0x40000
	s_addc_u32 s53, s53, 0
	v_pk_fma_f32 v[8:9], v[8:9], v[78:79], v[14:15]
	s_waitcnt vmcnt(45)
	v_cvt_pk_bf16_f32 v12, v8, v9
	global_store_dword v10, v12, s[54:55]
	s_add_u32 s54, s54, 0x40000
	s_addc_u32 s55, s55, 0
	v_lshlrev_b32_e32 v14, 16, v34
	v_and_b32_e32 v15, 0xffff0000, v34
	global_load_dword v34, v10, s[52:53]
	s_add_u32 s52, s52, 0x40000
	s_addc_u32 s53, s53, 0
	v_pk_fma_f32 v[8:9], v[8:9], v[80:81], v[14:15]
	s_waitcnt vmcnt(46)
	v_cvt_pk_bf16_f32 v13, v8, v9
	global_store_dword v10, v13, s[54:55]
	s_add_u32 s54, s54, 0x40000
	s_addc_u32 s55, s55, 0
	v_lshlrev_b32_e32 v14, 16, v35
	v_and_b32_e32 v15, 0xffff0000, v35
	global_load_dword v35, v10, s[52:53]
	s_add_u32 s52, s52, 0x40000
	s_addc_u32 s53, s53, 0
	v_pk_fma_f32 v[8:9], v[8:9], v[82:83], v[14:15]
	s_waitcnt lgkmcnt(0)
	ds_read_b64 v[68:69], v11 offset:12288
	ds_read_b64 v[70:71], v11 offset:12800
	ds_read_b64 v[72:73], v11 offset:13312
	ds_read_b64 v[74:75], v11 offset:13824
	ds_read_b64 v[76:77], v11 offset:14336
	ds_read_b64 v[78:79], v11 offset:14848
	ds_read_b64 v[80:81], v11 offset:15360
	ds_read_b64 v[82:83], v11 offset:15872
	s_waitcnt vmcnt(47)
	v_cvt_pk_bf16_f32 v12, v8, v9
	global_store_dword v10, v12, s[54:55]
	s_add_u32 s54, s54, 0x40000
	s_addc_u32 s55, s55, 0
	v_lshlrev_b32_e32 v14, 16, v36
	v_and_b32_e32 v15, 0xffff0000, v36
	global_load_dword v36, v10, s[52:53]
	s_add_u32 s52, s52, 0x40000
	s_addc_u32 s53, s53, 0
	v_pk_fma_f32 v[8:9], v[8:9], v[52:53], v[14:15]
	s_waitcnt vmcnt(48)
	v_cvt_pk_bf16_f32 v13, v8, v9
	global_store_dword v10, v13, s[54:55]
	s_add_u32 s54, s54, 0x40000
	s_addc_u32 s55, s55, 0
	v_lshlrev_b32_e32 v14, 16, v37
	v_and_b32_e32 v15, 0xffff0000, v37
	global_load_dword v37, v10, s[52:53]
	s_add_u32 s52, s52, 0x40000
	s_addc_u32 s53, s53, 0
	v_pk_fma_f32 v[8:9], v[8:9], v[54:55], v[14:15]
	s_waitcnt vmcnt(49)
; __device__ __forceinline__ float bflo(unsigned u) { return __uint_as_float(u << 16); }
; __device__ __forceinline__ float bfhi(unsigned u) { return __uint_as_float(u & 0xffff0000u); }
; __device__ __forceinline__ unsigned pk2(float lo, float hi) { return pg8::cvt_pk_bf16(lo, hi); }
; __device__ __forceinline__ void scan_phase(bf16* U, bf16* So, const float* DEC, int bid, int G, int tid) {
;     ...
;         for (int c0 = 0; c0 < NCH; c0 += SCAN_B) {
;             unsigned ub[SCAN_B]; f32x2 db[SCAN_B];
; #pragma unroll
;             for (int i = 0; i < SCAN_B; ++i) { ub[i] = up[(size_t)(c0 + i) * (NH * HV * HK / 2)]; db[i] = dp[(size_t)(c0 + i) * (DQK / 2)]; }
; #pragma unroll
;             for (int i = 0; i < SCAN_B; ++i) { op[(size_t)(c0 + i) * (NH * HV * HK / 2)] = pk2(s0, s1); s0 = db[i].x * s0 + bflo(ub[i]); s1 = db[i].y * s1 + bfhi(ub[i]); }
	v_cvt_pk_bf16_f32 v12, v8, v9
	global_store_dword v10, v12, s[54:55]
	s_add_u32 s54, s54, 0x40000
	s_addc_u32 s55, s55, 0
	v_lshlrev_b32_e32 v14, 16, v38
	v_and_b32_e32 v15, 0xffff0000, v38
	global_load_dword v38, v10, s[52:53]
	s_add_u32 s52, s52, 0x40000
	s_addc_u32 s53, s53, 0
	v_pk_fma_f32 v[8:9], v[8:9], v[56:57], v[14:15]
	s_waitcnt vmcnt(50)
	v_cvt_pk_bf16_f32 v13, v8, v9
	global_store_dword v10, v13, s[54:55]
	s_add_u32 s54, s54, 0x40000
	s_addc_u32 s55, s55, 0
	v_lshlrev_b32_e32 v14, 16, v39
	v_and_b32_e32 v15, 0xffff0000, v39
	global_load_dword v39, v10, s[52:53]
	s_add_u32 s52, s52, 0x40000
	s_addc_u32 s53, s53, 0
	v_pk_fma_f32 v[8:9], v[8:9], v[58:59], v[14:15]
	s_waitcnt vmcnt(51)
	v_cvt_pk_bf16_f32 v12, v8, v9
	global_store_dword v10, v12, s[54:55]
	s_add_u32 s54, s54, 0x40000
	s_addc_u32 s55, s55, 0
	v_lshlrev_b32_e32 v14, 16, v40
	v_and_b32_e32 v15, 0xffff0000, v40
	global_load_dword v40, v10, s[52:53]
	s_add_u32 s52, s52, 0x40000
	s_addc_u32 s53, s53, 0
	v_pk_fma_f32 v[8:9], v[8:9], v[60:61], v[14:15]
	s_waitcnt vmcnt(52)
	v_cvt_pk_bf16_f32 v13, v8, v9
	global_store_dword v10, v13, s[54:55]
	s_add_u32 s54, s54, 0x40000
	s_addc_u32 s55, s55, 0
	v_lshlrev_b32_e32 v14, 16, v41
	v_and_b32_e32 v15, 0xffff0000, v41
	global_load_dword v41, v10, s[52:53]
	s_add_u32 s52, s52, 0x40000
	s_addc_u32 s53, s53, 0
	v_pk_fma_f32 v[8:9], v[8:9], v[62:63], v[14:15]
	s_waitcnt vmcnt(53)
	v_cvt_pk_bf16_f32 v12, v8, v9
	global_store_dword v10, v12, s[54:55]
	s_add_u32 s54, s54, 0x40000
	s_addc_u32 s55, s55, 0
	v_lshlrev_b32_e32 v14, 16, v42
	v_and_b32_e32 v15, 0xffff0000, v42
	global_load_dword v42, v10, s[52:53]
	s_add_u32 s52, s52, 0x40000
	s_addc_u32 s53, s53, 0
	v_pk_fma_f32 v[8:9], v[8:9], v[64:65], v[14:15]
	s_waitcnt vmcnt(54)
	v_cvt_pk_bf16_f32 v13, v8, v9
	global_store_dword v10, v13, s[54:55]
	s_add_u32 s54, s54, 0x40000
	s_addc_u32 s55, s55, 0
	v_lshlrev_b32_e32 v14, 16, v43
	v_and_b32_e32 v15, 0xffff0000, v43
	global_load_dword v43, v10, s[52:53]
	s_add_u32 s52, s52, 0x40000
	s_addc_u32 s53, s53, 0
	v_pk_fma_f32 v[8:9], v[8:9], v[66:67], v[14:15]
	s_waitcnt lgkmcnt(0)
	ds_read_b64 v[52:53], v11 offset:16384
	ds_read_b64 v[54:55], v11 offset:16896
	ds_read_b64 v[56:57], v11 offset:17408
	ds_read_b64 v[58:59], v11 offset:17920
	ds_read_b64 v[60:61], v11 offset:18432
	ds_read_b64 v[62:63], v11 offset:18944
	ds_read_b64 v[64:65], v11 offset:19456
	ds_read_b64 v[66:67], v11 offset:19968
	s_waitcnt vmcnt(55)
	v_cvt_pk_bf16_f32 v12, v8, v9
	global_store_dword v10, v12, s[54:55]
	s_add_u32 s54, s54, 0x40000
	s_addc_u32 s55, s55, 0
	v_lshlrev_b32_e32 v14, 16, v44
	v_and_b32_e32 v15, 0xffff0000, v44
	global_load_dword v44, v10, s[52:53]
	s_add_u32 s52, s52, 0x40000
	s_addc_u32 s53, s53, 0
	v_pk_fma_f32 v[8:9], v[8:9], v[68:69], v[14:15]
	s_waitcnt vmcnt(56)
	v_cvt_pk_bf16_f32 v13, v8, v9
	global_store_dword v10, v13, s[54:55]
	s_add_u32 s54, s54, 0x40000
	s_addc_u32 s55, s55, 0
	v_lshlrev_b32_e32 v14, 16, v45
	v_and_b32_e32 v15, 0xffff0000, v45
	global_load_dword v45, v10, s[52:53]
	s_add_u32 s52, s52, 0x40000
	s_addc_u32 s53, s53, 0
	v_pk_fma_f32 v[8:9], v[8:9], v[70:71], v[14:15]
	s_waitcnt vmcnt(57)
	v_cvt_pk_bf16_f32 v12, v8, v9
	global_store_dword v10, v12, s[54:55]
	s_add_u32 s54, s54, 0x40000
	s_addc_u32 s55, s55, 0
	v_lshlrev_b32_e32 v14, 16, v46
	v_and_b32_e32 v15, 0xffff0000, v46
	global_load_dword v46, v10, s[52:53]
	s_add_u32 s52, s52, 0x40000
	s_addc_u32 s53, s53, 0
	v_pk_fma_f32 v[8:9], v[8:9], v[72:73], v[14:15]
	s_waitcnt vmcnt(58)
	v_cvt_pk_bf16_f32 v13, v8, v9
	global_store_dword v10, v13, s[54:55]
	s_add_u32 s54, s54, 0x40000
	s_addc_u32 s55, s55, 0
	v_lshlrev_b32_e32 v14, 16, v47
	v_and_b32_e32 v15, 0xffff0000, v47
	global_load_dword v47, v10, s[52:53]
	s_add_u32 s52, s52, 0x40000
	s_addc_u32 s53, s53, 0
	v_pk_fma_f32 v[8:9], v[8:9], v[74:75], v[14:15]
	s_waitcnt vmcnt(59)
	v_cvt_pk_bf16_f32 v12, v8, v9
	global_store_dword v10, v12, s[54:55]
	s_add_u32 s54, s54, 0x40000
	s_addc_u32 s55, s55, 0
	v_lshlrev_b32_e32 v14, 16, v48
	v_and_b32_e32 v15, 0xffff0000, v48
	global_load_dword v48, v10, s[52:53]
	s_add_u32 s52, s52, 0x40000
	s_addc_u32 s53, s53, 0
	v_pk_fma_f32 v[8:9], v[8:9], v[76:77], v[14:15]
	s_waitcnt vmcnt(60)
	v_cvt_pk_bf16_f32 v13, v8, v9
	global_store_dword v10, v13, s[54:55]
	s_add_u32 s54, s54, 0x40000
	s_addc_u32 s55, s55, 0
	v_lshlrev_b32_e32 v14, 16, v49
	v_and_b32_e32 v15, 0xffff0000, v49
	global_load_dword v49, v10, s[52:53]
	s_add_u32 s52, s52, 0x40000
	s_addc_u32 s53, s53, 0
	v_pk_fma_f32 v[8:9], v[8:9], v[78:79], v[14:15]
	s_waitcnt vmcnt(61)
	v_cvt_pk_bf16_f32 v12, v8, v9
	global_store_dword v10, v12, s[54:55]
	s_add_u32 s54, s54, 0x40000
	s_addc_u32 s55, s55, 0
	v_lshlrev_b32_e32 v14, 16, v50
	v_and_b32_e32 v15, 0xffff0000, v50
	global_load_dword v50, v10, s[52:53]
	s_add_u32 s52, s52, 0x40000
	s_addc_u32 s53, s53, 0
	v_pk_fma_f32 v[8:9], v[8:9], v[80:81], v[14:15]
	s_waitcnt vmcnt(62)
	v_cvt_pk_bf16_f32 v13, v8, v9
	global_store_dword v10, v13, s[54:55]
	s_add_u32 s54, s54, 0x40000
	s_addc_u32 s55, s55, 0
	v_lshlrev_b32_e32 v14, 16, v51
	v_and_b32_e32 v15, 0xffff0000, v51
	global_load_dword v51, v10, s[52:53]
	s_add_u32 s52, s52, 0x40000
	s_addc_u32 s53, s53, 0
	v_pk_fma_f32 v[8:9], v[8:9], v[82:83], v[14:15]
	v_add_u32_e32 v11, 0x4000, v11
	s_movk_i32 s27, 7
; __device__ __forceinline__ float bflo(unsigned u) { return __uint_as_float(u << 16); }
; __device__ __forceinline__ float bfhi(unsigned u) { return __uint_as_float(u & 0xffff0000u); }
; __device__ __forceinline__ unsigned pk2(float lo, float hi) { return pg8::cvt_pk_bf16(lo, hi); }
; __device__ __forceinline__ void scan_phase(bf16* U, bf16* So, const float* DEC, int bid, int G, int tid) {
;     ...
;         for (int c0 = 0; c0 < NCH; c0 += SCAN_B) {
;             unsigned ub[SCAN_B]; f32x2 db[SCAN_B];
; #pragma unroll
;             for (int i = 0; i < SCAN_B; ++i) { ub[i] = up[(size_t)(c0 + i) * (NH * HV * HK / 2)]; db[i] = dp[(size_t)(c0 + i) * (DQK / 2)]; }
; #pragma unroll
;             for (int i = 0; i < SCAN_B; ++i) { op[(size_t)(c0 + i) * (NH * HV * HK / 2)] = pk2(s0, s1); s0 = db[i].x * s0 + bflo(ub[i]); s1 = db[i].y * s1 + bfhi(ub[i]); }
.Lscan_loop:
	s_waitcnt lgkmcnt(0)
	ds_read_b64 v[68:69], v11 offset:4096
	ds_read_b64 v[70:71], v11 offset:4608
	ds_read_b64 v[72:73], v11 offset:5120
	ds_read_b64 v[74:75], v11 offset:5632
	ds_read_b64 v[76:77], v11 offset:6144
	ds_read_b64 v[78:79], v11 offset:6656
	ds_read_b64 v[80:81], v11 offset:7168
	ds_read_b64 v[82:83], v11 offset:7680
	s_waitcnt vmcnt(62)
	v_cvt_pk_bf16_f32 v12, v8, v9
	global_store_dword v10, v12, s[54:55]
	s_add_u32 s54, s54, 0x40000
	s_addc_u32 s55, s55, 0
	v_lshlrev_b32_e32 v14, 16, v20
	v_and_b32_e32 v15, 0xffff0000, v20
	global_load_dword v20, v10, s[52:53]
	s_add_u32 s52, s52, 0x40000
	s_addc_u32 s53, s53, 0
	v_pk_fma_f32 v[8:9], v[8:9], v[52:53], v[14:15]
	s_waitcnt vmcnt(62)
	v_cvt_pk_bf16_f32 v13, v8, v9
	global_store_dword v10, v13, s[54:55]
	s_add_u32 s54, s54, 0x40000
	s_addc_u32 s55, s55, 0
	v_lshlrev_b32_e32 v14, 16, v21
	v_and_b32_e32 v15, 0xffff0000, v21
	global_load_dword v21, v10, s[52:53]
	s_add_u32 s52, s52, 0x40000
	s_addc_u32 s53, s53, 0
	v_pk_fma_f32 v[8:9], v[8:9], v[54:55], v[14:15]
	s_waitcnt vmcnt(62)
	v_cvt_pk_bf16_f32 v12, v8, v9
	global_store_dword v10, v12, s[54:55]
	s_add_u32 s54, s54, 0x40000
	s_addc_u32 s55, s55, 0
	v_lshlrev_b32_e32 v14, 16, v22
	v_and_b32_e32 v15, 0xffff0000, v22
	global_load_dword v22, v10, s[52:53]
	s_add_u32 s52, s52, 0x40000
	s_addc_u32 s53, s53, 0
	v_pk_fma_f32 v[8:9], v[8:9], v[56:57], v[14:15]
	s_waitcnt vmcnt(62)
	v_cvt_pk_bf16_f32 v13, v8, v9
	global_store_dword v10, v13, s[54:55]
	s_add_u32 s54, s54, 0x40000
	s_addc_u32 s55, s55, 0
	v_lshlrev_b32_e32 v14, 16, v23
	v_and_b32_e32 v15, 0xffff0000, v23
	global_load_dword v23, v10, s[52:53]
	s_add_u32 s52, s52, 0x40000
	s_addc_u32 s53, s53, 0
	v_pk_fma_f32 v[8:9], v[8:9], v[58:59], v[14:15]
	s_waitcnt vmcnt(62)
	v_cvt_pk_bf16_f32 v12, v8, v9
	global_store_dword v10, v12, s[54:55]
	s_add_u32 s54, s54, 0x40000
	s_addc_u32 s55, s55, 0
	v_lshlrev_b32_e32 v14, 16, v24
	v_and_b32_e32 v15, 0xffff0000, v24
	global_load_dword v24, v10, s[52:53]
	s_add_u32 s52, s52, 0x40000
	s_addc_u32 s53, s53, 0
	v_pk_fma_f32 v[8:9], v[8:9], v[60:61], v[14:15]
	s_waitcnt vmcnt(62)
	v_cvt_pk_bf16_f32 v13, v8, v9
	global_store_dword v10, v13, s[54:55]
	s_add_u32 s54, s54, 0x40000
	s_addc_u32 s55, s55, 0
	v_lshlrev_b32_e32 v14, 16, v25
	v_and_b32_e32 v15, 0xffff0000, v25
	global_load_dword v25, v10, s[52:53]
	s_add_u32 s52, s52, 0x40000
	s_addc_u32 s53, s53, 0
	v_pk_fma_f32 v[8:9], v[8:9], v[62:63], v[14:15]
	s_waitcnt vmcnt(62)
	v_cvt_pk_bf16_f32 v12, v8, v9
	global_store_dword v10, v12, s[54:55]
	s_add_u32 s54, s54, 0x40000
	s_addc_u32 s55, s55, 0
	v_lshlrev_b32_e32 v14, 16, v26
	v_and_b32_e32 v15, 0xffff0000, v26
	global_load_dword v26, v10, s[52:53]
	s_add_u32 s52, s52, 0x40000
	s_addc_u32 s53, s53, 0
	v_pk_fma_f32 v[8:9], v[8:9], v[64:65], v[14:15]
	s_waitcnt vmcnt(62)
	v_cvt_pk_bf16_f32 v13, v8, v9
	global_store_dword v10, v13, s[54:55]
	s_add_u32 s54, s54, 0x40000
	s_addc_u32 s55, s55, 0
	v_lshlrev_b32_e32 v14, 16, v27
	v_and_b32_e32 v15, 0xffff0000, v27
	global_load_dword v27, v10, s[52:53]
	s_add_u32 s52, s52, 0x40000
	s_addc_u32 s53, s53, 0
	v_pk_fma_f32 v[8:9], v[8:9], v[66:67], v[14:15]
	s_waitcnt lgkmcnt(0)
	ds_read_b64 v[52:53], v11 offset:8192
	ds_read_b64 v[54:55], v11 offset:8704
	ds_read_b64 v[56:57], v11 offset:9216
	ds_read_b64 v[58:59], v11 offset:9728
	ds_read_b64 v[60:61], v11 offset:10240
	ds_read_b64 v[62:63], v11 offset:10752
	ds_read_b64 v[64:65], v11 offset:11264
	ds_read_b64 v[66:67], v11 offset:11776
	s_waitcnt vmcnt(62)
	v_cvt_pk_bf16_f32 v12, v8, v9
	global_store_dword v10, v12, s[54:55]
	s_add_u32 s54, s54, 0x40000
	s_addc_u32 s55, s55, 0
	v_lshlrev_b32_e32 v14, 16, v28
	v_and_b32_e32 v15, 0xffff0000, v28
	global_load_dword v28, v10, s[52:53]
	s_add_u32 s52, s52, 0x40000
	s_addc_u32 s53, s53, 0
	v_pk_fma_f32 v[8:9], v[8:9], v[68:69], v[14:15]
	s_waitcnt vmcnt(62)
	v_cvt_pk_bf16_f32 v13, v8, v9
	global_store_dword v10, v13, s[54:55]
	s_add_u32 s54, s54, 0x40000
	s_addc_u32 s55, s55, 0
	v_lshlrev_b32_e32 v14, 16, v29
	v_and_b32_e32 v15, 0xffff0000, v29
	global_load_dword v29, v10, s[52:53]
	s_add_u32 s52, s52, 0x40000
	s_addc_u32 s53, s53, 0
	v_pk_fma_f32 v[8:9], v[8:9], v[70:71], v[14:15]
	s_waitcnt vmcnt(62)
	v_cvt_pk_bf16_f32 v12, v8, v9
	global_store_dword v10, v12, s[54:55]
	s_add_u32 s54, s54, 0x40000
	s_addc_u32 s55, s55, 0
	v_lshlrev_b32_e32 v14, 16, v30
	v_and_b32_e32 v15, 0xffff0000, v30
	global_load_dword v30, v10, s[52:53]
	s_add_u32 s52, s52, 0x40000
	s_addc_u32 s53, s53, 0
	v_pk_fma_f32 v[8:9], v[8:9], v[72:73], v[14:15]
	s_waitcnt vmcnt(62)
	v_cvt_pk_bf16_f32 v13, v8, v9
	global_store_dword v10, v13, s[54:55]
	s_add_u32 s54, s54, 0x40000
	s_addc_u32 s55, s55, 0
	v_lshlrev_b32_e32 v14, 16, v31
	v_and_b32_e32 v15, 0xffff0000, v31
	global_load_dword v31, v10, s[52:53]
	s_add_u32 s52, s52, 0x40000
	s_addc_u32 s53, s53, 0
	v_pk_fma_f32 v[8:9], v[8:9], v[74:75], v[14:15]
	s_waitcnt vmcnt(62)
	v_cvt_pk_bf16_f32 v12, v8, v9
	global_store_dword v10, v12, s[54:55]
	s_add_u32 s54, s54, 0x40000
	s_addc_u32 s55, s55, 0
	v_lshlrev_b32_e32 v14, 16, v32
	v_and_b32_e32 v15, 0xffff0000, v32
	global_load_dword v32, v10, s[52:53]
	s_add_u32 s52, s52, 0x40000
	s_addc_u32 s53, s53, 0
	v_pk_fma_f32 v[8:9], v[8:9], v[76:77], v[14:15]
	s_waitcnt vmcnt(62)
	v_cvt_pk_bf16_f32 v13, v8, v9
	global_store_dword v10, v13, s[54:55]
	s_add_u32 s54, s54, 0x40000
	s_addc_u32 s55, s55, 0
	v_lshlrev_b32_e32 v14, 16, v33
	v_and_b32_e32 v15, 0xffff0000, v33
	global_load_dword v33, v10, s[52:53]
	s_add_u32 s52, s52, 0x40000
	s_addc_u32 s53, s53, 0
	v_pk_fma_f32 v[8:9], v[8:9], v[78:79], v[14:15]
	s_waitcnt vmcnt(62)
; __device__ __forceinline__ float bflo(unsigned u) { return __uint_as_float(u << 16); }
; __device__ __forceinline__ float bfhi(unsigned u) { return __uint_as_float(u & 0xffff0000u); }
; __device__ __forceinline__ unsigned pk2(float lo, float hi) { return pg8::cvt_pk_bf16(lo, hi); }
; __device__ __forceinline__ void scan_phase(bf16* U, bf16* So, const float* DEC, int bid, int G, int tid) {
;     ...
;         for (int c0 = 0; c0 < NCH; c0 += SCAN_B) {
;             unsigned ub[SCAN_B]; f32x2 db[SCAN_B];
; #pragma unroll
;             for (int i = 0; i < SCAN_B; ++i) { ub[i] = up[(size_t)(c0 + i) * (NH * HV * HK / 2)]; db[i] = dp[(size_t)(c0 + i) * (DQK / 2)]; }
; #pragma unroll
;             for (int i = 0; i < SCAN_B; ++i) { op[(size_t)(c0 + i) * (NH * HV * HK / 2)] = pk2(s0, s1); s0 = db[i].x * s0 + bflo(ub[i]); s1 = db[i].y * s1 + bfhi(ub[i]); }
	v_cvt_pk_bf16_f32 v12, v8, v9
	global_store_dword v10, v12, s[54:55]
	s_add_u32 s54, s54, 0x40000
	s_addc_u32 s55, s55, 0
	v_lshlrev_b32_e32 v14, 16, v34
	v_and_b32_e32 v15, 0xffff0000, v34
	global_load_dword v34, v10, s[52:53]
	s_add_u32 s52, s52, 0x40000
	s_addc_u32 s53, s53, 0
	v_pk_fma_f32 v[8:9], v[8:9], v[80:81], v[14:15]
	s_waitcnt vmcnt(62)
	v_cvt_pk_bf16_f32 v13, v8, v9
	global_store_dword v10, v13, s[54:55]
	s_add_u32 s54, s54, 0x40000
	s_addc_u32 s55, s55, 0
	v_lshlrev_b32_e32 v14, 16, v35
	v_and_b32_e32 v15, 0xffff0000, v35
	global_load_dword v35, v10, s[52:53]
	s_add_u32 s52, s52, 0x40000
	s_addc_u32 s53, s53, 0
	v_pk_fma_f32 v[8:9], v[8:9], v[82:83], v[14:15]
	s_waitcnt lgkmcnt(0)
	ds_read_b64 v[68:69], v11 offset:12288
	ds_read_b64 v[70:71], v11 offset:12800
	ds_read_b64 v[72:73], v11 offset:13312
	ds_read_b64 v[74:75], v11 offset:13824
	ds_read_b64 v[76:77], v11 offset:14336
	ds_read_b64 v[78:79], v11 offset:14848
	ds_read_b64 v[80:81], v11 offset:15360
	ds_read_b64 v[82:83], v11 offset:15872
	s_waitcnt vmcnt(62)
	v_cvt_pk_bf16_f32 v12, v8, v9
	global_store_dword v10, v12, s[54:55]
	s_add_u32 s54, s54, 0x40000
	s_addc_u32 s55, s55, 0
	v_lshlrev_b32_e32 v14, 16, v36
	v_and_b32_e32 v15, 0xffff0000, v36
	global_load_dword v36, v10, s[52:53]
	s_add_u32 s52, s52, 0x40000
	s_addc_u32 s53, s53, 0
	v_pk_fma_f32 v[8:9], v[8:9], v[52:53], v[14:15]
	s_waitcnt vmcnt(62)
	v_cvt_pk_bf16_f32 v13, v8, v9
	global_store_dword v10, v13, s[54:55]
	s_add_u32 s54, s54, 0x40000
	s_addc_u32 s55, s55, 0
	v_lshlrev_b32_e32 v14, 16, v37
	v_and_b32_e32 v15, 0xffff0000, v37
	global_load_dword v37, v10, s[52:53]
	s_add_u32 s52, s52, 0x40000
	s_addc_u32 s53, s53, 0
	v_pk_fma_f32 v[8:9], v[8:9], v[54:55], v[14:15]
	s_waitcnt vmcnt(62)
	v_cvt_pk_bf16_f32 v12, v8, v9
	global_store_dword v10, v12, s[54:55]
	s_add_u32 s54, s54, 0x40000
	s_addc_u32 s55, s55, 0
	v_lshlrev_b32_e32 v14, 16, v38
	v_and_b32_e32 v15, 0xffff0000, v38
	global_load_dword v38, v10, s[52:53]
	s_add_u32 s52, s52, 0x40000
	s_addc_u32 s53, s53, 0
	v_pk_fma_f32 v[8:9], v[8:9], v[56:57], v[14:15]
	s_waitcnt vmcnt(62)
	v_cvt_pk_bf16_f32 v13, v8, v9
	global_store_dword v10, v13, s[54:55]
	s_add_u32 s54, s54, 0x40000
	s_addc_u32 s55, s55, 0
	v_lshlrev_b32_e32 v14, 16, v39
	v_and_b32_e32 v15, 0xffff0000, v39
	global_load_dword v39, v10, s[52:53]
	s_add_u32 s52, s52, 0x40000
	s_addc_u32 s53, s53, 0
	v_pk_fma_f32 v[8:9], v[8:9], v[58:59], v[14:15]
	s_waitcnt vmcnt(62)
	v_cvt_pk_bf16_f32 v12, v8, v9
	global_store_dword v10, v12, s[54:55]
	s_add_u32 s54, s54, 0x40000
	s_addc_u32 s55, s55, 0
	v_lshlrev_b32_e32 v14, 16, v40
	v_and_b32_e32 v15, 0xffff0000, v40
	global_load_dword v40, v10, s[52:53]
	s_add_u32 s52, s52, 0x40000
	s_addc_u32 s53, s53, 0
	v_pk_fma_f32 v[8:9], v[8:9], v[60:61], v[14:15]
	s_waitcnt vmcnt(62)
	v_cvt_pk_bf16_f32 v13, v8, v9
	global_store_dword v10, v13, s[54:55]
	s_add_u32 s54, s54, 0x40000
	s_addc_u32 s55, s55, 0
	v_lshlrev_b32_e32 v14, 16, v41
	v_and_b32_e32 v15, 0xffff0000, v41
	global_load_dword v41, v10, s[52:53]
	s_add_u32 s52, s52, 0x40000
	s_addc_u32 s53, s53, 0
	v_pk_fma_f32 v[8:9], v[8:9], v[62:63], v[14:15]
	s_waitcnt vmcnt(62)
	v_cvt_pk_bf16_f32 v12, v8, v9
	global_store_dword v10, v12, s[54:55]
	s_add_u32 s54, s54, 0x40000
	s_addc_u32 s55, s55, 0
	v_lshlrev_b32_e32 v14, 16, v42
	v_and_b32_e32 v15, 0xffff0000, v42
	global_load_dword v42, v10, s[52:53]
	s_add_u32 s52, s52, 0x40000
	s_addc_u32 s53, s53, 0
	v_pk_fma_f32 v[8:9], v[8:9], v[64:65], v[14:15]
	s_waitcnt vmcnt(62)
; __device__ __forceinline__ float bflo(unsigned u) { return __uint_as_float(u << 16); }
; __device__ __forceinline__ float bfhi(unsigned u) { return __uint_as_float(u & 0xffff0000u); }
; __device__ __forceinline__ unsigned pk2(float lo, float hi) { return pg8::cvt_pk_bf16(lo, hi); }
; __device__ __forceinline__ void scan_phase(bf16* U, bf16* So, const float* DEC, int bid, int G, int tid) {
;     ...
;         for (int c0 = 0; c0 < NCH; c0 += SCAN_B) {
;             unsigned ub[SCAN_B]; f32x2 db[SCAN_B];
; #pragma unroll
;             for (int i = 0; i < SCAN_B; ++i) { ub[i] = up[(size_t)(c0 + i) * (NH * HV * HK / 2)]; db[i] = dp[(size_t)(c0 + i) * (DQK / 2)]; }
; #pragma unroll
;             for (int i = 0; i < SCAN_B; ++i) { op[(size_t)(c0 + i) * (NH * HV * HK / 2)] = pk2(s0, s1); s0 = db[i].x * s0 + bflo(ub[i]); s1 = db[i].y * s1 + bfhi(ub[i]); }
	v_cvt_pk_bf16_f32 v13, v8, v9
	global_store_dword v10, v13, s[54:55]
	s_add_u32 s54, s54, 0x40000
	s_addc_u32 s55, s55, 0
	v_lshlrev_b32_e32 v14, 16, v43
	v_and_b32_e32 v15, 0xffff0000, v43
	global_load_dword v43, v10, s[52:53]
	s_add_u32 s52, s52, 0x40000
	s_addc_u32 s53, s53, 0
	v_pk_fma_f32 v[8:9], v[8:9], v[66:67], v[14:15]
	s_waitcnt lgkmcnt(0)
	ds_read_b64 v[52:53], v11 offset:16384
	ds_read_b64 v[54:55], v11 offset:16896
	ds_read_b64 v[56:57], v11 offset:17408
	ds_read_b64 v[58:59], v11 offset:17920
	ds_read_b64 v[60:61], v11 offset:18432
	ds_read_b64 v[62:63], v11 offset:18944
	ds_read_b64 v[64:65], v11 offset:19456
	ds_read_b64 v[66:67], v11 offset:19968
	s_waitcnt vmcnt(62)
	v_cvt_pk_bf16_f32 v12, v8, v9
	global_store_dword v10, v12, s[54:55]
	s_add_u32 s54, s54, 0x40000
	s_addc_u32 s55, s55, 0
	v_lshlrev_b32_e32 v14, 16, v44
	v_and_b32_e32 v15, 0xffff0000, v44
	global_load_dword v44, v10, s[52:53]
	s_add_u32 s52, s52, 0x40000
	s_addc_u32 s53, s53, 0
	v_pk_fma_f32 v[8:9], v[8:9], v[68:69], v[14:15]
	s_waitcnt vmcnt(62)
	v_cvt_pk_bf16_f32 v13, v8, v9
	global_store_dword v10, v13, s[54:55]
	s_add_u32 s54, s54, 0x40000
	s_addc_u32 s55, s55, 0
	v_lshlrev_b32_e32 v14, 16, v45
	v_and_b32_e32 v15, 0xffff0000, v45
	global_load_dword v45, v10, s[52:53]
	s_add_u32 s52, s52, 0x40000
	s_addc_u32 s53, s53, 0
	v_pk_fma_f32 v[8:9], v[8:9], v[70:71], v[14:15]
	s_waitcnt vmcnt(62)
	v_cvt_pk_bf16_f32 v12, v8, v9
	global_store_dword v10, v12, s[54:55]
	s_add_u32 s54, s54, 0x40000
	s_addc_u32 s55, s55, 0
	v_lshlrev_b32_e32 v14, 16, v46
	v_and_b32_e32 v15, 0xffff0000, v46
	global_load_dword v46, v10, s[52:53]
	s_add_u32 s52, s52, 0x40000
	s_addc_u32 s53, s53, 0
	v_pk_fma_f32 v[8:9], v[8:9], v[72:73], v[14:15]
	s_waitcnt vmcnt(62)
	v_cvt_pk_bf16_f32 v13, v8, v9
	global_store_dword v10, v13, s[54:55]
	s_add_u32 s54, s54, 0x40000
	s_addc_u32 s55, s55, 0
	v_lshlrev_b32_e32 v14, 16, v47
	v_and_b32_e32 v15, 0xffff0000, v47
	global_load_dword v47, v10, s[52:53]
	s_add_u32 s52, s52, 0x40000
	s_addc_u32 s53, s53, 0
	v_pk_fma_f32 v[8:9], v[8:9], v[74:75], v[14:15]
	s_waitcnt vmcnt(62)
	v_cvt_pk_bf16_f32 v12, v8, v9
	global_store_dword v10, v12, s[54:55]
	s_add_u32 s54, s54, 0x40000
	s_addc_u32 s55, s55, 0
	v_lshlrev_b32_e32 v14, 16, v48
	v_and_b32_e32 v15, 0xffff0000, v48
	global_load_dword v48, v10, s[52:53]
	s_add_u32 s52, s52, 0x40000
	s_addc_u32 s53, s53, 0
	v_pk_fma_f32 v[8:9], v[8:9], v[76:77], v[14:15]
	s_waitcnt vmcnt(62)
	v_cvt_pk_bf16_f32 v13, v8, v9
	global_store_dword v10, v13, s[54:55]
	s_add_u32 s54, s54, 0x40000
	s_addc_u32 s55, s55, 0
	v_lshlrev_b32_e32 v14, 16, v49
	v_and_b32_e32 v15, 0xffff0000, v49
	global_load_dword v49, v10, s[52:53]
	s_add_u32 s52, s52, 0x40000
	s_addc_u32 s53, s53, 0
	v_pk_fma_f32 v[8:9], v[8:9], v[78:79], v[14:15]
	s_waitcnt vmcnt(62)
	v_cvt_pk_bf16_f32 v12, v8, v9
	global_store_dword v10, v12, s[54:55]
	s_add_u32 s54, s54, 0x40000
	s_addc_u32 s55, s55, 0
	v_lshlrev_b32_e32 v14, 16, v50
	v_and_b32_e32 v15, 0xffff0000, v50
	global_load_dword v50, v10, s[52:53]
	s_add_u32 s52, s52, 0x40000
	s_addc_u32 s53, s53, 0
	v_pk_fma_f32 v[8:9], v[8:9], v[80:81], v[14:15]
	s_waitcnt vmcnt(62)
	v_cvt_pk_bf16_f32 v13, v8, v9
	global_store_dword v10, v13, s[54:55]
	s_add_u32 s54, s54, 0x40000
	s_addc_u32 s55, s55, 0
	v_lshlrev_b32_e32 v14, 16, v51
	v_and_b32_e32 v15, 0xffff0000, v51
	global_load_dword v51, v10, s[52:53]
	s_add_u32 s52, s52, 0x40000
	s_addc_u32 s53, s53, 0
	v_pk_fma_f32 v[8:9], v[8:9], v[82:83], v[14:15]
	v_add_u32_e32 v11, 0x4000, v11
	s_sub_u32 s27, s27, 1
	s_cmp_lg_u32 s27, 0
	s_cbranch_scc1 .Lscan_loop
